# phase 4 token loop: next-token prefetch loads issued just before the table wait (vmcnt(8)) instead of at the loop top, so the wait no longer forces them
# baseline (speedup 1.0000x reference)
.LBB0_1171:
	s_waitcnt vmcnt(0)
	s_or_b64 exec, exec, s[12:13]
	v_readlane_b32 s12, v245, 42
	v_readlane_b32 s13, v245, 43
	v_mov_b64_e32 v[76:77], v[62:63]
	v_mov_b64_e32 v[74:75], v[60:61]
	v_lshl_add_u64 v[42:43], v[42:43], 0, s[12:13]
	v_readlane_b32 s12, v245, 44
	v_readlane_b32 s13, v245, 45
	v_mov_b64_e32 v[72:73], v[64:65]
	v_mov_b64_e32 v[70:71], v[66:67]
	v_lshl_add_u64 v[44:45], v[44:45], 0, s[12:13]
	v_readlane_b32 s12, v245, 48
	v_readlane_b32 s13, v245, 49
	s_add_u32 s44, s44, s12
	s_addc_u32 s45, s45, s13
	v_readlane_b32 s12, v245, 46
	v_readlane_b32 s13, v245, 47
	v_mov_b32_e32 v68, v58
	v_mov_b64_e32 v[30:31], v[2:3]
	v_lshl_add_u64 v[46:47], v[46:47], 0, s[12:13]
	v_mov_b64_e32 v[32:33], v[4:5]
	v_mov_b64_e32 v[26:27], v[6:7]
	v_mov_b64_e32 v[28:29], v[8:9]
	v_mov_b64_e32 v[22:23], v[14:15]
	v_mov_b64_e32 v[24:25], v[16:17]
	s_waitcnt lgkmcnt(0)
	v_mov_b64_e32 v[18:19], v[10:11]
	v_mov_b64_e32 v[20:21], v[12:13]
	s_andn2_b64 exec, exec, s[42:43]
	s_cbranch_execz .LBB0_1180
.LBB0_1172:
	s_movk_i32 s0, 0xfff
	v_cmp_lt_i32_e32 vcc, s0, v68
	v_add_u32_e32 v58, s12, v68
	s_movk_i32 s0, 0x2fff
	v_cmp_gt_i32_e64 s[12:13], s96, v58
	v_cmp_lt_i32_e64 s[38:39], s0, v58
	s_mov_b64 s[70:71], 0
	s_and_saveexec_b64 s[46:47], s[12:13]
	s_cbranch_execz .LBB0_1178
	s_movk_i32 s0, 0xfff
	v_cmp_lt_i32_e64 s[12:13], s0, v58
	s_and_saveexec_b64 s[48:49], s[12:13]
	s_xor_b64 s[12:13], exec, s[48:49]
	v_add_u32_e32 v0, 0xfffff000, v58
	v_lshlrev_b64 v[2:3], 12, v[0:1]
	v_mov_b32_e32 v59, v1
	v_lshl_add_u64 v[2:3], s[40:41], 0, v[2:3]
	v_mov_b64_e32 v[4:5], v[58:59]
	s_andn2_saveexec_b64 s[12:13], s[12:13]
	v_lshl_add_u64 v[2:3], v[48:49], 0, s[44:45]
	v_mov_b64_e32 v[4:5], v[46:47]
	s_or_b64 exec, exec, s[12:13]
	v_lshlrev_b64 v[4:5], 11, v[4:5]
	v_lshlrev_b32_e32 v0, 2, v34
	v_lshl_add_u64 v[10:11], v[40:41], 0, v[4:5]
	v_lshl_add_u64 v[12:13], v[2:3], 0, v[0:1]
	s_mov_b64 s[70:71], exec
.LBB0_1178:
	s_or_b64 exec, exec, s[46:47]
	v_add_u32_e32 v0, 0xfffff000, v68
	v_lshlrev_b32_e32 v68, 16, v76
	v_and_b32_e32 v69, 0xffff0000, v76
	s_mov_b32 s0, 0x3fb504f3
	v_lshlrev_b32_e32 v76, 16, v77
	v_and_b32_e32 v77, 0xffff0000, v77
	v_pk_fma_f32 v[30:31], v[30:31], s[0:1], v[68:69] op_sel_hi:[1,0,1]
	v_lshlrev_b32_e32 v68, 16, v74
	v_and_b32_e32 v69, 0xffff0000, v74
	v_pk_fma_f32 v[32:33], v[32:33], s[0:1], v[76:77] op_sel_hi:[1,0,1]
	v_add_f32_e32 v53, v30, v31
	v_lshlrev_b32_e32 v74, 16, v75
	v_and_b32_e32 v75, 0xffff0000, v75
	v_pk_fma_f32 v[68:69], v[26:27], s[0:1], v[68:69] op_sel_hi:[1,0,1]
	v_add_f32_e32 v53, v53, v32
	v_pk_fma_f32 v[74:75], v[28:29], s[0:1], v[74:75] op_sel_hi:[1,0,1]
	v_add_f32_e32 v26, v68, v69
	v_add_f32_e32 v53, v33, v53
	v_add_f32_e32 v26, v26, v74
	v_add_f32_e32 v53, 0, v53
	v_add_f32_e32 v26, v75, v26
	v_add_f32_e32 v53, v53, v26
	v_lshlrev_b32_e32 v26, 16, v72
	v_and_b32_e32 v27, 0xffff0000, v72
	v_lshlrev_b32_e32 v28, 16, v73
	v_and_b32_e32 v29, 0xffff0000, v73
	v_pk_fma_f32 v[72:73], v[22:23], s[0:1], v[26:27] op_sel_hi:[1,0,1]
	v_pk_fma_f32 v[76:77], v[24:25], s[0:1], v[28:29] op_sel_hi:[1,0,1]
	v_add_f32_e32 v22, v72, v73
	v_add_f32_e32 v22, v22, v76
	v_add_f32_e32 v22, v77, v22
	v_add_f32_e32 v26, v53, v22
	v_lshlrev_b32_e32 v22, 16, v70
	v_and_b32_e32 v23, 0xffff0000, v70
	v_lshlrev_b32_e32 v24, 16, v71
	v_and_b32_e32 v25, 0xffff0000, v71
	v_pk_fma_f32 v[70:71], v[18:19], s[0:1], v[22:23] op_sel_hi:[1,0,1]
	v_lshrrev_b32_e32 v0, 11, v0
	v_pk_fma_f32 v[84:85], v[20:21], s[0:1], v[24:25] op_sel_hi:[1,0,1]
	v_add_f32_e32 v18, v70, v71
	v_add_u32_e32 v0, 1, v0
	v_add_f32_e32 v18, v18, v84
	v_readlane_b32 s48, v247, 49
	v_cndmask_b32_e32 v0, 0, v0, vcc
	v_add_f32_e32 v18, v85, v18
	v_readlane_b32 s50, v247, 51
	v_readlane_b32 s51, v247, 52
	v_add_u32_e32 v0, s68, v0
	s_and_b64 s[12:13], exec, s[38:39]
	v_add_f32_e32 v22, v26, v18
	v_mov_b64_e32 v[18:19], s[50:51]
	s_or_b64 s[42:43], s[12:13], s[42:43]
	v_mad_u64_u32 v[20:21], s[12:13], v0, s97, v[18:19]
	ds_bpermute_b32 v0, v35, v22
	s_mov_b64 s[12:13], 0x4000
	v_mov_b32_e32 v53, v1
	s_mov_b32 s0, 0x800000
	v_mov_b32_e32 v55, v1
	s_waitcnt lgkmcnt(0)
	v_add_f32_e32 v0, v22, v0
	ds_bpermute_b32 v18, v78, v0
	v_lshl_add_u64 v[22:23], v[50:51], 0, s[44:45]
	v_mov_b32_e32 v57, v1
	v_readlane_b32 s49, v247, 50
	v_readlane_b32 s52, v247, 53
	s_waitcnt lgkmcnt(0)
	v_add_f32_e32 v0, v0, v18
	ds_bpermute_b32 v18, v79, v0
	v_readlane_b32 s53, v247, 54
	v_readlane_b32 s54, v247, 55
	v_readlane_b32 s55, v247, 56
	v_readlane_b32 s56, v247, 57
	s_waitcnt lgkmcnt(0)
	v_add_f32_e32 v0, v0, v18
	ds_bpermute_b32 v18, v80, v0
	v_readlane_b32 s57, v247, 58
	v_readlane_b32 s58, v247, 59
	v_readlane_b32 s59, v247, 60
	v_readlane_b32 s60, v247, 61
	s_waitcnt lgkmcnt(0)
	v_add_f32_e32 v0, v0, v18
	ds_bpermute_b32 v18, v81, v0
	v_readlane_b32 s61, v247, 62
	v_readlane_b32 s62, v247, 63
	v_readlane_b32 s63, v246, 0
	s_waitcnt lgkmcnt(0)
	v_add_f32_e32 v0, v0, v18
	ds_bpermute_b32 v18, v82, v0
	s_waitcnt lgkmcnt(0)
	v_add_f32_e32 v0, v0, v18
	v_mul_f32_e32 v86, 0x3a800000, v0
	v_pk_add_f32 v[88:89], v[30:31], v[86:87] op_sel_hi:[1,0] neg_lo:[0,1] neg_hi:[0,1]
	global_load_dwordx4 v[24:27], v[36:37], off
	global_load_dwordx4 v[28:31], v[38:39], off
	v_pk_add_f32 v[94:95], v[68:69], v[86:87] op_sel_hi:[1,0] neg_lo:[0,1] neg_hi:[0,1]
	v_pk_add_f32 v[96:97], v[74:75], v[86:87] op_sel_hi:[1,0] neg_lo:[0,1] neg_hi:[0,1]
	v_mov_b32_e32 v74, v89
	v_mov_b32_e32 v75, v95
	v_pk_add_f32 v[102:103], v[72:73], v[86:87] op_sel_hi:[1,0] neg_lo:[0,1] neg_hi:[0,1]
	v_pk_add_f32 v[108:109], v[70:71], v[86:87] op_sel_hi:[1,0] neg_lo:[0,1] neg_hi:[0,1]
	v_pk_add_f32 v[32:33], v[32:33], v[86:87] op_sel_hi:[1,0] neg_lo:[0,1] neg_hi:[0,1]
	v_mov_b32_e32 v68, v88
	v_mov_b32_e32 v69, v94
	v_pk_mul_f32 v[74:75], v[74:75], v[74:75]
	v_mov_b32_e32 v72, v109
	v_mov_b32_e32 v73, v103
	v_pk_fma_f32 v[68:69], v[68:69], v[68:69], v[74:75]
	v_mov_b32_e32 v74, v32
	v_mov_b32_e32 v75, v96
	v_pk_add_f32 v[76:77], v[76:77], v[86:87] op_sel_hi:[1,0] neg_lo:[0,1] neg_hi:[0,1]
	v_pk_add_f32 v[110:111], v[84:85], v[86:87] op_sel_hi:[1,0] neg_lo:[0,1] neg_hi:[0,1]
	v_mov_b32_e32 v70, v108
	v_mov_b32_e32 v71, v102
	v_pk_mul_f32 v[72:73], v[72:73], v[72:73]
	v_lshl_add_u64 v[18:19], v[20:21], 0, s[12:13]
	s_mov_b64 s[12:13], 0x3000
	v_mov_b32_e32 v98, v33
	v_mov_b32_e32 v99, v97
	v_pk_fma_f32 v[68:69], v[74:75], v[74:75], v[68:69]
	v_pk_fma_f32 v[70:71], v[70:71], v[70:71], v[72:73]
	v_mov_b32_e32 v72, v110
	v_mov_b32_e32 v73, v76
	v_lshl_add_u64 v[20:21], v[20:21], 0, s[12:13]
	v_lshlrev_b32_e32 v0, 2, v34
	v_pk_fma_f32 v[68:69], v[98:99], v[98:99], v[68:69]
	v_mov_b32_e32 v74, v111
	v_mov_b32_e32 v75, v77
	v_pk_fma_f32 v[70:71], v[72:73], v[72:73], v[70:71]
	v_lshl_add_u64 v[90:91], v[18:19], 0, v[0:1]
	v_lshl_add_u64 v[92:93], v[20:21], 0, v[0:1]
	v_pk_fma_f32 v[70:71], v[74:75], v[74:75], v[70:71]
	v_add_f32_e32 v0, v68, v69
	v_add_f32_e32 v0, v71, v0
	v_add_f32_e32 v0, v70, v0
	v_lshl_add_u64 v[98:99], v[18:19], 0, v[52:53]
	v_lshl_add_u64 v[100:101], v[20:21], 0, v[52:53]
	ds_bpermute_b32 v53, v35, v0
	v_lshl_add_u64 v[104:105], v[18:19], 0, v[54:55]
	v_lshl_add_u64 v[106:107], v[20:21], 0, v[54:55]
	v_lshl_add_u64 v[18:19], v[18:19], 0, v[56:57]
	global_load_dwordx4 v[112:115], v[90:91], off
	global_load_dwordx4 v[116:119], v[92:93], off
	global_load_dwordx4 v[120:123], v[36:37], off offset:1024
	global_load_dwordx4 v[124:127], v[38:39], off offset:1024
	global_load_dwordx4 v[128:131], v[98:99], off
	global_load_dwordx4 v[132:135], v[100:101], off
	global_load_dwordx4 v[136:139], v[36:37], off offset:2048
	global_load_dwordx4 v[160:163], v[38:39], off offset:2048
	global_load_dwordx4 v[164:167], v[104:105], off
	global_load_dwordx4 v[168:171], v[106:107], off
	global_load_dwordx4 v[172:175], v[36:37], off offset:3072
	global_load_dwordx4 v[176:179], v[38:39], off offset:3072
	global_load_dwordx4 v[216:219], v[18:19], off
	v_lshl_add_u64 v[224:225], v[20:21], 0, v[56:57]
	global_load_dwordx4 v[220:223], v[224:225], off
	s_waitcnt lgkmcnt(0)
	v_add_f32_e32 v0, v0, v53
	ds_bpermute_b32 v53, v78, v0
	s_waitcnt lgkmcnt(0)
	v_add_f32_e32 v0, v0, v53
	ds_bpermute_b32 v53, v79, v0
	s_waitcnt lgkmcnt(0)
	v_add_f32_e32 v0, v0, v53
	ds_bpermute_b32 v53, v80, v0
	s_waitcnt lgkmcnt(0)
	v_add_f32_e32 v0, v0, v53
	ds_bpermute_b32 v53, v81, v0
	s_waitcnt lgkmcnt(0)
	v_add_f32_e32 v0, v0, v53
	ds_bpermute_b32 v53, v82, v0
	s_waitcnt lgkmcnt(0)
	v_add_f32_e32 v0, v0, v53
	v_fmamk_f32 v0, v0, 0x3a800000, v210
	v_cmp_gt_f32_e32 vcc, s0, v0
	v_mul_f32_e32 v53, 0x4b800000, v0
	s_nop 0
	v_cndmask_b32_e32 v0, v0, v53, vcc
	v_rsq_f32_e32 v0, v0
	s_nop 0
	v_mul_f32_e32 v53, 0x45800000, v0
	v_cndmask_b32_e32 v0, v0, v53, vcc
	v_pk_mul_f32 v[68:69], v[88:89], v[0:1] op_sel_hi:[1,0]
	s_cmp_eq_u64 s[70:71], 0
	s_cbranch_scc1 .Lp4_nopf
	s_mov_b64 s[72:73], exec
	s_mov_b64 exec, s[70:71]
	global_load_dwordx4 v[2:5], v[12:13], off
	global_load_dwordx4 v[6:9], v[12:13], off offset:1024
	global_load_dwordx2 v[62:63], v[10:11], off
	global_load_dwordx2 v[60:61], v[10:11], off offset:512
	global_load_dwordx2 v[64:65], v[10:11], off offset:1024
	global_load_dwordx2 v[66:67], v[10:11], off offset:1536
	global_load_dwordx4 v[14:17], v[12:13], off offset:2048
	global_load_dwordx4 v[10:13], v[12:13], off offset:3072
	s_mov_b64 exec, s[72:73]
	s_waitcnt vmcnt(8)
	s_branch .Lp4_pfdone

.Lp4_pfdone:
	v_pk_fma_f32 v[28:29], v[24:25], v[68:69], v[28:29]
	v_pk_mul_f32 v[24:25], v[32:33], v[0:1] op_sel_hi:[1,0]
	s_nop 0
	v_pk_fma_f32 v[30:31], v[26:27], v[24:25], v[30:31]
	global_store_dwordx4 v[22:23], v[28:31], off
	v_pk_add_f32 v[24:25], v[112:113], 1.0 op_sel_hi:[1,0]
	s_nop 0
	v_pk_fma_f32 v[26:27], v[24:25], v[28:29], v[116:117]
	v_pk_add_f32 v[24:25], v[114:115], 1.0 op_sel_hi:[1,0]
	s_nop 0
	v_pk_fma_f32 v[28:29], v[24:25], v[30:31], v[118:119]
	v_cvt_pk_bf16_f32 v24, v26, v27
	v_cvt_pk_bf16_f32 v25, v28, v29
	global_store_dwordx2 v[44:45], v[24:25], off
	v_pk_mul_f32 v[24:25], v[94:95], v[0:1] op_sel_hi:[1,0]
	s_nop 0
	v_pk_fma_f32 v[30:31], v[24:25], v[120:121], v[124:125]
	v_pk_mul_f32 v[24:25], v[96:97], v[0:1] op_sel_hi:[1,0]
	s_nop 0
	v_pk_fma_f32 v[32:33], v[24:25], v[122:123], v[126:127]
	global_store_dwordx4 v[22:23], v[30:33], off offset:1024
	v_pk_add_f32 v[24:25], v[128:129], 1.0 op_sel_hi:[1,0]
	s_nop 1
	v_pk_fma_f32 v[30:31], v[30:31], v[24:25], v[132:133]
	v_pk_add_f32 v[24:25], v[130:131], 1.0 op_sel_hi:[1,0]
	s_nop 0
	v_pk_fma_f32 v[32:33], v[32:33], v[24:25], v[134:135]
	v_cvt_pk_bf16_f32 v24, v30, v31
	v_cvt_pk_bf16_f32 v25, v32, v33
	global_store_dwordx2 v[44:45], v[24:25], off offset:512
	v_pk_mul_f32 v[24:25], v[102:103], v[0:1] op_sel_hi:[1,0]
	s_nop 0
	v_pk_fma_f32 v[68:69], v[24:25], v[136:137], v[160:161]
	v_pk_mul_f32 v[24:25], v[76:77], v[0:1] op_sel_hi:[1,0]
	s_nop 0
	v_pk_fma_f32 v[70:71], v[24:25], v[138:139], v[162:163]
	global_store_dwordx4 v[22:23], v[68:71], off offset:2048
	v_pk_add_f32 v[24:25], v[164:165], 1.0 op_sel_hi:[1,0]
	s_nop 1
	v_pk_fma_f32 v[68:69], v[68:69], v[24:25], v[168:169]
	v_pk_add_f32 v[24:25], v[166:167], 1.0 op_sel_hi:[1,0]
	s_nop 0
	v_pk_fma_f32 v[70:71], v[70:71], v[24:25], v[170:171]
	v_cvt_pk_bf16_f32 v24, v68, v69
	v_cvt_pk_bf16_f32 v25, v70, v71
	global_store_dwordx2 v[44:45], v[24:25], off offset:1024
	v_pk_mul_f32 v[24:25], v[108:109], v[0:1] op_sel_hi:[1,0]
	s_nop 0
	v_pk_fma_f32 v[84:85], v[24:25], v[172:173], v[176:177]
	v_pk_mul_f32 v[24:25], v[110:111], v[0:1] op_sel_hi:[1,0]
	s_nop 0
	v_pk_fma_f32 v[86:87], v[24:25], v[174:175], v[178:179]
	global_store_dwordx4 v[22:23], v[84:87], off offset:3072
	v_pk_add_f32 v[18:19], v[216:217], 1.0 op_sel_hi:[1,0]
	s_nop 1
	v_pk_fma_f32 v[74:75], v[84:85], v[18:19], v[220:221]
	v_pk_add_f32 v[18:19], v[218:219], 1.0 op_sel_hi:[1,0]
	s_nop 0
	v_pk_fma_f32 v[72:73], v[86:87], v[18:19], v[222:223]
	v_cvt_pk_bf16_f32 v18, v74, v75
	v_cvt_pk_bf16_f32 v19, v72, v73
	global_store_dwordx2 v[44:45], v[18:19], off offset:1536
	ds_read_b128 v[18:21], v83
	s_waitcnt lgkmcnt(0)
	v_mul_f32_e32 v0, v27, v19
	v_fmac_f32_e32 v0, v26, v18
	v_fmac_f32_e32 v0, v28, v20
	v_fmac_f32_e32 v0, v29, v21
	ds_read_b128 v[18:21], v83 offset:1024
	v_add_f32_e32 v0, 0, v0
	s_waitcnt lgkmcnt(0)
	v_mul_f32_e32 v19, v31, v19
	v_fmac_f32_e32 v19, v30, v18
	v_fmac_f32_e32 v19, v32, v20
	v_fmac_f32_e32 v19, v33, v21
	v_add_f32_e32 v0, v0, v19
	ds_read_b128 v[18:21], v83 offset:2048
	s_waitcnt lgkmcnt(0)
	v_mul_f32_e32 v19, v69, v19
	v_fmac_f32_e32 v19, v68, v18
	v_fmac_f32_e32 v19, v70, v20
	v_fmac_f32_e32 v19, v71, v21
	v_add_f32_e32 v0, v0, v19
	ds_read_b128 v[18:21], v83 offset:3072
	s_waitcnt lgkmcnt(0)
	v_mul_f32_e32 v19, v75, v19
	v_fmac_f32_e32 v19, v74, v18
	v_fmac_f32_e32 v19, v72, v20
	v_fmac_f32_e32 v19, v73, v21
	v_add_f32_e32 v0, v0, v19
	ds_read_b128 v[18:21], v83 offset:7168
	ds_read_b128 v[22:25], v83 offset:6144
	ds_read_b128 v[84:87], v83 offset:5120
	ds_read_b128 v[88:91], v83 offset:4096
	s_waitcnt lgkmcnt(3)
	v_mul_f32_e32 v18, v74, v18
	s_waitcnt lgkmcnt(2)
	v_mul_f32_e32 v22, v68, v22
	s_waitcnt lgkmcnt(1)
	v_mul_f32_e32 v55, v30, v84
	s_waitcnt lgkmcnt(0)
	v_mul_f32_e32 v53, v26, v88
	v_fmac_f32_e32 v53, v27, v89
	v_fmac_f32_e32 v53, v28, v90
	v_fmac_f32_e32 v55, v31, v85
	v_fmac_f32_e32 v53, v29, v91
	v_fmac_f32_e32 v55, v32, v86
	v_fmac_f32_e32 v22, v69, v23
	v_add_f32_e32 v53, 0, v53
	v_fmac_f32_e32 v55, v33, v87
	v_fmac_f32_e32 v22, v70, v24
	v_fmac_f32_e32 v18, v75, v19
	v_add_f32_e32 v53, v55, v53
	v_fmac_f32_e32 v22, v71, v25
	v_fmac_f32_e32 v18, v72, v20
	v_add_f32_e32 v22, v22, v53
	v_fmac_f32_e32 v18, v73, v21
	v_add_f32_e32 v53, v18, v22
	ds_read_b128 v[18:21], v83 offset:11264
	ds_read_b128 v[22:25], v83 offset:10240
	ds_read_b128 v[84:87], v83 offset:9216
	ds_read_b128 v[88:91], v83 offset:8192
	s_waitcnt lgkmcnt(3)
	v_mul_f32_e32 v18, v74, v18
	s_waitcnt lgkmcnt(2)
	v_mul_f32_e32 v22, v68, v22
	s_waitcnt lgkmcnt(1)
	v_mul_f32_e32 v57, v30, v84
	s_waitcnt lgkmcnt(0)
	v_mul_f32_e32 v55, v26, v88
	v_fmac_f32_e32 v55, v27, v89
	v_fmac_f32_e32 v55, v28, v90
	v_fmac_f32_e32 v57, v31, v85
	v_fmac_f32_e32 v55, v29, v91
	v_fmac_f32_e32 v57, v32, v86
	v_fmac_f32_e32 v22, v69, v23
	v_add_f32_e32 v55, 0, v55
	v_fmac_f32_e32 v57, v33, v87
	v_fmac_f32_e32 v22, v70, v24
	v_fmac_f32_e32 v18, v75, v19
	v_add_f32_e32 v55, v57, v55
	v_fmac_f32_e32 v22, v71, v25
	v_fmac_f32_e32 v18, v72, v20
	v_add_f32_e32 v22, v22, v55
	v_fmac_f32_e32 v18, v73, v21
	v_add_f32_e32 v55, v18, v22
	ds_read_b128 v[18:21], v83 offset:15360
	ds_read_b128 v[22:25], v83 offset:14336
	ds_read_b128 v[84:87], v83 offset:13312
	ds_read_b128 v[88:91], v83 offset:12288
	s_waitcnt lgkmcnt(3)
	v_mul_f32_e32 v18, v74, v18
	s_waitcnt lgkmcnt(2)
	v_mul_f32_e32 v22, v68, v22
	s_waitcnt lgkmcnt(1)
	v_mul_f32_e32 v59, v30, v84
	s_waitcnt lgkmcnt(0)
	v_mul_f32_e32 v57, v26, v88
	v_fmac_f32_e32 v57, v27, v89
	v_fmac_f32_e32 v57, v28, v90
	v_fmac_f32_e32 v59, v31, v85
	v_fmac_f32_e32 v57, v29, v91
	v_fmac_f32_e32 v59, v32, v86
	v_fmac_f32_e32 v22, v69, v23
	v_add_f32_e32 v57, 0, v57
	v_fmac_f32_e32 v59, v33, v87
	v_fmac_f32_e32 v22, v70, v24
	v_fmac_f32_e32 v18, v75, v19
	v_add_f32_e32 v57, v59, v57
	v_fmac_f32_e32 v22, v71, v25
	v_fmac_f32_e32 v18, v72, v20
	v_add_f32_e32 v22, v22, v57
	v_fmac_f32_e32 v18, v73, v21
	v_add_f32_e32 v18, v18, v22
	ds_read_b128 v[20:23], v83 offset:16384
	ds_read_b128 v[84:87], v83 offset:17408
	ds_read_b128 v[88:91], v83 offset:18432
	s_waitcnt lgkmcnt(2)
	v_mul_f32_e32 v19, v27, v21
	s_waitcnt lgkmcnt(1)
	v_mul_f32_e32 v21, v31, v85
	v_fmac_f32_e32 v19, v26, v20
	v_fmac_f32_e32 v21, v30, v84
	v_fmac_f32_e32 v19, v28, v22
	v_fmac_f32_e32 v19, v29, v23
	v_fmac_f32_e32 v21, v32, v86
	v_add_f32_e32 v19, 0, v19
	v_fmac_f32_e32 v21, v33, v87
	v_add_f32_e32 v19, v19, v21
	ds_read_b128 v[20:23], v83 offset:19456
	s_waitcnt lgkmcnt(1)
	v_mul_f32_e32 v24, v69, v89
	v_fmac_f32_e32 v24, v68, v88
	v_fmac_f32_e32 v24, v70, v90
	v_fmac_f32_e32 v24, v71, v91
	ds_read_b128 v[84:87], v83 offset:21504
	ds_read_b128 v[88:91], v83 offset:20480
	s_waitcnt lgkmcnt(2)
	v_mul_f32_e32 v21, v75, v21
	v_fmac_f32_e32 v21, v74, v20
	v_fmac_f32_e32 v21, v72, v22
	v_add_f32_e32 v19, v19, v24
	v_fmac_f32_e32 v21, v73, v23
	v_add_f32_e32 v19, v19, v21
	ds_read_b128 v[20:23], v83 offset:23552
	ds_read_b128 v[92:95], v83 offset:22528
	s_waitcnt lgkmcnt(2)
	v_mul_f32_e32 v24, v26, v88
	v_fmac_f32_e32 v24, v27, v89
	v_mul_f32_e32 v25, v30, v84
	v_fmac_f32_e32 v24, v28, v90
	v_fmac_f32_e32 v25, v31, v85
	v_fmac_f32_e32 v24, v29, v91
	v_fmac_f32_e32 v25, v32, v86
	v_add_f32_e32 v24, 0, v24
	v_fmac_f32_e32 v25, v33, v87
	v_add_f32_e32 v24, v25, v24
	s_waitcnt lgkmcnt(0)
	v_mul_f32_e32 v25, v68, v92
	ds_read_b128 v[84:87], v83 offset:25600
	ds_read_b128 v[88:91], v83 offset:24576
	v_fmac_f32_e32 v25, v69, v93
	v_mul_f32_e32 v20, v74, v20
	v_fmac_f32_e32 v25, v70, v94
	v_fmac_f32_e32 v20, v75, v21
	v_fmac_f32_e32 v25, v71, v95
	v_fmac_f32_e32 v20, v72, v22
	v_add_f32_e32 v24, v25, v24
	v_fmac_f32_e32 v20, v73, v23
	v_add_f32_e32 v24, v20, v24
	ds_read_b128 v[20:23], v83 offset:27648
	ds_read_b128 v[92:95], v83 offset:26624
	s_waitcnt lgkmcnt(2)
	v_mul_f32_e32 v25, v26, v88
	v_fmac_f32_e32 v25, v27, v89
	v_mul_f32_e32 v57, v30, v84
	v_fmac_f32_e32 v25, v28, v90
	v_fmac_f32_e32 v57, v31, v85
	v_fmac_f32_e32 v25, v29, v91
	v_fmac_f32_e32 v57, v32, v86
	v_add_f32_e32 v25, 0, v25
	v_fmac_f32_e32 v57, v33, v87
	v_add_f32_e32 v25, v57, v25
	s_waitcnt lgkmcnt(0)
	v_mul_f32_e32 v57, v68, v92
	ds_read_b128 v[84:87], v83 offset:29696
	ds_read_b128 v[88:91], v83 offset:28672
	v_fmac_f32_e32 v57, v69, v93
	v_mul_f32_e32 v20, v74, v20
	v_fmac_f32_e32 v57, v70, v94
	v_fmac_f32_e32 v20, v75, v21
	v_fmac_f32_e32 v57, v71, v95
	v_fmac_f32_e32 v20, v72, v22
	v_add_f32_e32 v25, v57, v25
	v_fmac_f32_e32 v20, v73, v23
	v_add_f32_e32 v25, v20, v25
	ds_read_b128 v[20:23], v83 offset:31744
	ds_read_b128 v[92:95], v83 offset:30720
	s_waitcnt lgkmcnt(2)
	v_mul_f32_e32 v57, v26, v88
	v_fmac_f32_e32 v57, v27, v89
	v_mul_f32_e32 v59, v30, v84
	v_fmac_f32_e32 v57, v28, v90
	v_fmac_f32_e32 v59, v31, v85
	v_fmac_f32_e32 v57, v29, v91
	v_fmac_f32_e32 v59, v32, v86
	v_add_f32_e32 v57, 0, v57
	v_fmac_f32_e32 v59, v33, v87
	v_add_f32_e32 v57, v59, v57
	s_waitcnt lgkmcnt(0)
	v_mul_f32_e32 v59, v68, v92
	v_fmac_f32_e32 v59, v69, v93
	v_mul_f32_e32 v20, v74, v20
	v_fmac_f32_e32 v59, v70, v94
	v_fmac_f32_e32 v20, v75, v21
	v_fmac_f32_e32 v59, v71, v95
	v_fmac_f32_e32 v20, v72, v22
	v_add_f32_e32 v57, v59, v57
	v_fmac_f32_e32 v20, v73, v23
	v_add_f32_e32 v57, v20, v57
	ds_read_b128 v[20:23], v83 offset:32768
	ds_read_b128 v[84:87], v83 offset:33792
	ds_read_b128 v[88:91], v83 offset:34816
	s_waitcnt lgkmcnt(2)
	v_mul_f32_e32 v21, v27, v21
	s_waitcnt lgkmcnt(1)
	v_mul_f32_e32 v59, v31, v85
	v_fmac_f32_e32 v21, v26, v20
	v_fmac_f32_e32 v59, v30, v84
	v_fmac_f32_e32 v21, v28, v22
	v_fmac_f32_e32 v21, v29, v23
	v_fmac_f32_e32 v59, v32, v86
	v_add_f32_e32 v20, 0, v21
	v_fmac_f32_e32 v59, v33, v87
	v_add_f32_e32 v59, v20, v59
	ds_read_b128 v[20:23], v83 offset:35840
	s_waitcnt lgkmcnt(1)
	v_mul_f32_e32 v76, v69, v89
	v_fmac_f32_e32 v76, v68, v88
	v_fmac_f32_e32 v76, v70, v90
	v_fmac_f32_e32 v76, v71, v91
	ds_read_b128 v[84:87], v83 offset:37888
	ds_read_b128 v[88:91], v83 offset:36864
	s_waitcnt lgkmcnt(2)
	v_mul_f32_e32 v21, v75, v21
	v_fmac_f32_e32 v21, v74, v20
	v_fmac_f32_e32 v21, v72, v22
	v_add_f32_e32 v59, v59, v76
	v_fmac_f32_e32 v21, v73, v23
	v_add_f32_e32 v59, v59, v21
	ds_read_b128 v[20:23], v83 offset:39936
	ds_read_b128 v[92:95], v83 offset:38912
	s_waitcnt lgkmcnt(2)
	v_mul_f32_e32 v76, v26, v88
	v_fmac_f32_e32 v76, v27, v89
	v_mul_f32_e32 v77, v30, v84
	v_fmac_f32_e32 v76, v28, v90
	v_fmac_f32_e32 v77, v31, v85
	v_fmac_f32_e32 v76, v29, v91
	v_fmac_f32_e32 v77, v32, v86
	v_add_f32_e32 v76, 0, v76
	v_fmac_f32_e32 v77, v33, v87
	v_add_f32_e32 v76, v77, v76
	s_waitcnt lgkmcnt(0)
	v_mul_f32_e32 v77, v68, v92
	ds_read_b128 v[84:87], v83 offset:41984
	ds_read_b128 v[88:91], v83 offset:40960
	v_fmac_f32_e32 v77, v69, v93
	v_mul_f32_e32 v20, v74, v20
	v_fmac_f32_e32 v77, v70, v94
	v_fmac_f32_e32 v20, v75, v21
	v_fmac_f32_e32 v77, v71, v95
	v_fmac_f32_e32 v20, v72, v22
	v_add_f32_e32 v76, v77, v76
	v_fmac_f32_e32 v20, v73, v23
	v_add_f32_e32 v76, v20, v76
	ds_read_b128 v[20:23], v83 offset:44032
	ds_read_b128 v[92:95], v83 offset:43008
	s_waitcnt lgkmcnt(2)
	v_mul_f32_e32 v77, v26, v88
	v_fmac_f32_e32 v77, v27, v89
	v_mul_f32_e32 v84, v30, v84
	v_fmac_f32_e32 v77, v28, v90
	v_fmac_f32_e32 v84, v31, v85
	v_fmac_f32_e32 v77, v29, v91
	v_fmac_f32_e32 v84, v32, v86
	v_add_f32_e32 v77, 0, v77
	v_fmac_f32_e32 v84, v33, v87
	v_add_f32_e32 v77, v84, v77
	s_waitcnt lgkmcnt(0)
	v_mul_f32_e32 v84, v68, v92
	v_fmac_f32_e32 v84, v69, v93
	v_fmac_f32_e32 v84, v70, v94
	v_mul_f32_e32 v20, v74, v20
	v_fmac_f32_e32 v84, v71, v95
	v_fmac_f32_e32 v20, v75, v21
	v_add_f32_e32 v77, v84, v77
	v_fmac_f32_e32 v20, v72, v22
	ds_read_b128 v[84:87], v83 offset:46080
	ds_read_b128 v[88:91], v83 offset:45056
	v_fmac_f32_e32 v20, v73, v23
	v_add_f32_e32 v77, v20, v77
	ds_read_b128 v[20:23], v83 offset:48128
	ds_read_b128 v[92:95], v83 offset:47104
	s_waitcnt lgkmcnt(3)
	v_mul_f32_e32 v84, v30, v84
	s_waitcnt lgkmcnt(2)
	v_mul_f32_e32 v88, v26, v88
	v_fmac_f32_e32 v88, v27, v89
	v_fmac_f32_e32 v88, v28, v90
	v_fmac_f32_e32 v84, v31, v85
	s_waitcnt lgkmcnt(0)
	v_mul_f32_e32 v85, v68, v92
	v_fmac_f32_e32 v88, v29, v91
	v_fmac_f32_e32 v84, v32, v86
	v_fmac_f32_e32 v85, v69, v93
	v_mul_f32_e32 v20, v74, v20
	v_add_f32_e32 v88, 0, v88
	v_fmac_f32_e32 v84, v33, v87
	v_fmac_f32_e32 v85, v70, v94
	v_fmac_f32_e32 v20, v75, v21
	v_add_f32_e32 v84, v84, v88
	v_fmac_f32_e32 v85, v71, v95
	v_fmac_f32_e32 v20, v72, v22
	v_add_f32_e32 v84, v85, v84
	v_fmac_f32_e32 v20, v73, v23
	v_add_f32_e32 v96, v20, v84
	ds_read_b128 v[20:23], v83 offset:49152
	ds_read_b128 v[84:87], v83 offset:50176
	ds_read_b128 v[88:91], v83 offset:51200
	s_waitcnt lgkmcnt(2)
	v_mul_f32_e32 v21, v27, v21
	s_waitcnt lgkmcnt(1)
	v_mul_f32_e32 v85, v31, v85
	v_fmac_f32_e32 v21, v26, v20
	v_fmac_f32_e32 v85, v30, v84
	v_fmac_f32_e32 v21, v28, v22
	v_fmac_f32_e32 v21, v29, v23
	v_fmac_f32_e32 v85, v32, v86
	v_add_f32_e32 v20, 0, v21
	v_fmac_f32_e32 v85, v33, v87
	v_add_f32_e32 v84, v20, v85
	ds_read_b128 v[20:23], v83 offset:52224
	s_waitcnt lgkmcnt(1)
	v_mul_f32_e32 v85, v69, v89
	v_fmac_f32_e32 v85, v68, v88
	v_fmac_f32_e32 v85, v70, v90
	v_fmac_f32_e32 v85, v71, v91
	s_waitcnt lgkmcnt(0)
	v_mul_f32_e32 v21, v75, v21
	v_fmac_f32_e32 v21, v74, v20
	v_add_f32_e32 v92, v84, v85
	v_fmac_f32_e32 v21, v72, v22
	ds_read_b128 v[84:87], v83 offset:54272
	ds_read_b128 v[88:91], v83 offset:53248
	v_fmac_f32_e32 v21, v73, v23
	v_add_f32_e32 v97, v92, v21
	ds_read_b128 v[20:23], v83 offset:56320
	ds_read_b128 v[92:95], v83 offset:55296
	s_waitcnt lgkmcnt(3)
	v_mul_f32_e32 v84, v30, v84
	s_waitcnt lgkmcnt(2)
	v_mul_f32_e32 v88, v26, v88
	v_fmac_f32_e32 v88, v27, v89
	v_fmac_f32_e32 v88, v28, v90
	v_fmac_f32_e32 v84, v31, v85
	s_waitcnt lgkmcnt(0)
	v_mul_f32_e32 v85, v68, v92
	v_fmac_f32_e32 v88, v29, v91
	v_fmac_f32_e32 v84, v32, v86
	v_fmac_f32_e32 v85, v69, v93
	v_add_f32_e32 v88, 0, v88
	v_fmac_f32_e32 v84, v33, v87
	v_fmac_f32_e32 v85, v70, v94
	v_mul_f32_e32 v20, v74, v20
	v_add_f32_e32 v84, v84, v88
	v_fmac_f32_e32 v85, v71, v95
	v_fmac_f32_e32 v20, v75, v21
	v_add_f32_e32 v92, v85, v84
	v_fmac_f32_e32 v20, v72, v22
	ds_read_b128 v[84:87], v83 offset:58368
	ds_read_b128 v[88:91], v83 offset:57344
	v_fmac_f32_e32 v20, v73, v23
	v_add_f32_e32 v98, v20, v92
	ds_read_b128 v[20:23], v83 offset:60416
	ds_read_b128 v[92:95], v83 offset:59392
	s_waitcnt lgkmcnt(3)
	v_mul_f32_e32 v84, v30, v84
	s_waitcnt lgkmcnt(2)
	v_mul_f32_e32 v88, v26, v88
	v_fmac_f32_e32 v88, v27, v89
	v_fmac_f32_e32 v88, v28, v90
	v_fmac_f32_e32 v84, v31, v85
	s_waitcnt lgkmcnt(0)
	v_mul_f32_e32 v85, v68, v92
	v_fmac_f32_e32 v88, v29, v91
	v_fmac_f32_e32 v84, v32, v86
	v_fmac_f32_e32 v85, v69, v93
	v_add_f32_e32 v88, 0, v88
	v_fmac_f32_e32 v84, v33, v87
	v_fmac_f32_e32 v85, v70, v94
	v_add_f32_e32 v84, v84, v88
	v_fmac_f32_e32 v85, v71, v95
	v_add_f32_e32 v92, v85, v84
	ds_read_b128 v[84:87], v83 offset:62464
	ds_read_b128 v[88:91], v83 offset:61440
	v_mul_f32_e32 v20, v74, v20
	v_fmac_f32_e32 v20, v75, v21
	v_fmac_f32_e32 v20, v72, v22
	v_fmac_f32_e32 v20, v73, v23
	v_add_f32_e32 v99, v20, v92
	ds_read_b128 v[20:23], v83 offset:64512
	ds_read_b128 v[92:95], v83 offset:63488
	s_waitcnt lgkmcnt(2)
	v_mul_f32_e32 v26, v26, v88
	v_fmac_f32_e32 v26, v27, v89
	v_mul_f32_e32 v27, v30, v84
	v_fmac_f32_e32 v26, v28, v90
	v_fmac_f32_e32 v27, v31, v85
	v_fmac_f32_e32 v26, v29, v91
	v_fmac_f32_e32 v27, v32, v86
	v_add_f32_e32 v26, 0, v26
	v_fmac_f32_e32 v27, v33, v87
	v_add_f32_e32 v26, v27, v26
	s_waitcnt lgkmcnt(0)
	v_mul_f32_e32 v27, v68, v92
	v_fmac_f32_e32 v27, v69, v93
	v_mul_f32_e32 v20, v74, v20
	v_fmac_f32_e32 v27, v70, v94
	v_fmac_f32_e32 v20, v75, v21
	v_fmac_f32_e32 v27, v71, v95
	v_fmac_f32_e32 v20, v72, v22
	v_add_f32_e32 v26, v27, v26
	v_fmac_f32_e32 v20, v73, v23
	v_add_f32_e32 v20, v20, v26
	v_cndmask_b32_e64 v21, v0, v59, s[10:11]
	ds_bpermute_b32 v21, v35, v21
	v_cndmask_b32_e64 v0, v59, v0, s[10:11]
	v_cndmask_b32_e64 v22, v76, v53, s[10:11]
	v_cndmask_b32_e64 v23, v77, v55, s[10:11]
	s_waitcnt lgkmcnt(0)
	v_add_f32_e32 v0, v0, v21
	v_cndmask_b32_e64 v21, v53, v76, s[10:11]
	ds_bpermute_b32 v21, v35, v21
	s_waitcnt lgkmcnt(0)
	v_add_f32_e32 v21, v22, v21
	v_cndmask_b32_e64 v22, v55, v77, s[10:11]
	ds_bpermute_b32 v22, v35, v22
	s_waitcnt lgkmcnt(0)
	v_add_f32_e32 v22, v23, v22
	v_cndmask_b32_e64 v23, v18, v96, s[10:11]
	ds_bpermute_b32 v23, v35, v23
	v_cndmask_b32_e64 v18, v96, v18, s[10:11]
	s_waitcnt lgkmcnt(0)
	v_add_f32_e32 v18, v18, v23
	v_cndmask_b32_e64 v23, v19, v97, s[10:11]
	ds_bpermute_b32 v23, v35, v23
	v_cndmask_b32_e64 v19, v97, v19, s[10:11]
	s_waitcnt lgkmcnt(0)
	v_add_f32_e32 v19, v19, v23
	v_cndmask_b32_e64 v23, v24, v98, s[10:11]
	ds_bpermute_b32 v23, v35, v23
	v_cndmask_b32_e64 v24, v98, v24, s[10:11]
	s_waitcnt lgkmcnt(0)
	v_add_f32_e32 v23, v24, v23
	v_cndmask_b32_e64 v24, v25, v99, s[10:11]
	ds_bpermute_b32 v24, v35, v24
	v_cndmask_b32_e64 v25, v99, v25, s[10:11]
	s_waitcnt lgkmcnt(0)
	v_add_f32_e32 v24, v25, v24
	v_cndmask_b32_e64 v25, v57, v20, s[10:11]
	ds_bpermute_b32 v25, v35, v25
	v_cndmask_b32_e64 v20, v20, v57, s[10:11]
	s_waitcnt lgkmcnt(0)
	v_add_f32_e32 v20, v20, v25
	v_cndmask_b32_e64 v25, v0, v19, s[4:5]
	v_cndmask_b32_e64 v0, v19, v0, s[4:5]
	ds_bpermute_b32 v19, v78, v25
	s_waitcnt lgkmcnt(0)
	v_add_f32_e32 v0, v0, v19
	v_cndmask_b32_e64 v19, v21, v23, s[4:5]
	ds_bpermute_b32 v19, v78, v19
	v_cndmask_b32_e64 v21, v23, v21, s[4:5]
	s_waitcnt lgkmcnt(0)
	v_add_f32_e32 v19, v21, v19
	v_cndmask_b32_e64 v21, v22, v24, s[4:5]
	ds_bpermute_b32 v21, v78, v21
	v_cndmask_b32_e64 v22, v24, v22, s[4:5]
	s_waitcnt lgkmcnt(0)
	v_add_f32_e32 v21, v22, v21
	v_cndmask_b32_e64 v22, v18, v20, s[4:5]
	v_cndmask_b32_e64 v18, v20, v18, s[4:5]
	ds_bpermute_b32 v20, v78, v22
	s_waitcnt lgkmcnt(0)
	v_add_f32_e32 v18, v18, v20
	v_cndmask_b32_e64 v20, v0, v21, s[6:7]
	ds_bpermute_b32 v20, v79, v20
	v_cndmask_b32_e64 v0, v21, v0, s[6:7]
	s_waitcnt lgkmcnt(0)
	v_add_f32_e32 v0, v0, v20
	v_cndmask_b32_e64 v20, v19, v18, s[6:7]
	v_cndmask_b32_e64 v18, v18, v19, s[6:7]
	ds_bpermute_b32 v19, v79, v20
	s_waitcnt lgkmcnt(0)
	v_add_f32_e32 v18, v18, v19
	v_cndmask_b32_e64 v19, v0, v18, s[8:9]
	v_cndmask_b32_e64 v0, v18, v0, s[8:9]
	ds_bpermute_b32 v18, v80, v19
	s_waitcnt lgkmcnt(0)
	v_add_f32_e32 v0, v0, v18
	ds_bpermute_b32 v18, v81, v0
	s_waitcnt lgkmcnt(0)
	v_add_f32_e32 v0, v0, v18
	ds_bpermute_b32 v18, v82, v0
	s_waitcnt lgkmcnt(0)
	v_add_f32_e32 v0, v0, v18
	ds_bpermute_b32 v18, v35, v0
	s_waitcnt lgkmcnt(0)
	v_max_f32_e32 v18, v18, v18
	v_max_f32_e32 v18, v0, v18
	ds_bpermute_b32 v19, v78, v18
	s_waitcnt lgkmcnt(0)
	v_max_f32_e32 v19, v19, v19
	v_max_f32_e32 v18, v18, v19
	ds_bpermute_b32 v19, v79, v18
	s_waitcnt lgkmcnt(0)
	v_max_f32_e32 v19, v19, v19
	v_max_f32_e32 v18, v18, v19
	ds_bpermute_b32 v19, v80, v18
	s_waitcnt lgkmcnt(0)
	v_max_f32_e32 v19, v19, v19
	v_max_f32_e32 v18, v18, v19
	v_sub_f32_e32 v0, v0, v18
	v_mul_f32_e32 v0, 0x3fb8aa3b, v0
	v_exp_f32_e32 v0, v0
	ds_bpermute_b32 v18, v35, v0
	s_waitcnt lgkmcnt(0)
	v_add_f32_e32 v18, v0, v18
	ds_bpermute_b32 v19, v78, v18
	s_waitcnt lgkmcnt(0)
	v_add_f32_e32 v18, v18, v19
	ds_bpermute_b32 v19, v79, v18
	s_waitcnt lgkmcnt(0)
	v_add_f32_e32 v18, v18, v19
	ds_bpermute_b32 v19, v80, v18
	s_and_saveexec_b64 s[12:13], s[36:37]
	s_cbranch_execz .LBB0_1171
	s_waitcnt lgkmcnt(0)
	v_add_f32_e32 v18, v18, v19
	v_div_scale_f32 v19, s[38:39], v18, v18, v0
	v_rcp_f32_e32 v20, v19
	v_div_scale_f32 v21, vcc, v0, v18, v0
	v_readlane_b32 s48, v247, 49
	v_fma_f32 v22, -v19, v20, 1.0
	v_fmac_f32_e32 v20, v22, v20
	v_mul_f32_e32 v22, v21, v20
	v_fma_f32 v23, -v19, v22, v21
	v_fmac_f32_e32 v22, v23, v20
	v_fma_f32 v19, -v19, v22, v21
	v_div_fmas_f32 v19, v19, v20, v22
	v_readlane_b32 s60, v247, 61
	v_readlane_b32 s61, v247, 62
	v_div_fixup_f32 v0, v19, v18, v0
	v_readlane_b32 s49, v247, 50
	v_lshl_add_u64 v[18:19], s[60:61], 0, v[42:43]
	global_store_dword v[18:19], v0, off
	v_lshl_add_u64 v[18:19], s[92:93], 0, v[42:43]
	v_readlane_b32 s50, v247, 51
	v_readlane_b32 s51, v247, 52
	v_readlane_b32 s52, v247, 53
	v_readlane_b32 s53, v247, 54
	v_readlane_b32 s54, v247, 55
	v_readlane_b32 s55, v247, 56
	v_readlane_b32 s56, v247, 57
	v_readlane_b32 s57, v247, 58
	v_readlane_b32 s58, v247, 59
	v_readlane_b32 s59, v247, 60
	v_readlane_b32 s62, v247, 63
	v_readlane_b32 s63, v246, 0
	global_store_dword v[18:19], v211, off
	s_branch .LBB0_1171
